# p2: history rows of the row items fetched up front, pass-0 item rebalancing; p4: odd XCDs walk their item list in reverse
# speedup vs baseline: 1.1368x; 1.0093x over previous
; DEVI void phase2(const Params& P, int l, int pass, char* smem) {
;     ...
;   const int ntok = pass ? 8192 : 8448, base = pass ? 8448 : 0;
;   const int nck = pass ? 128 : 136;
;   const int nH = nck * 8;
;   const int total = nH + ntok / 4;
;   for (int id = blockIdx.x; id < total; id += gridDim.x) {
;     if (id < nH) h1_item(P, l, id >> 3, id & 7, smem, tid);
;     else mixab_row4(P, l, base, (id - nH) * 4, tid);
;   }
.LBB0_341:
	s_cmpk_eq_i32 s78, 0x440
	s_cbranch_scc0 .Lp2_plain
	s_cmpk_eq_i32 s23, 0x200
	s_cbranch_scc0 .Lp2_plain
	s_cmpk_eq_i32 s2, 0xc80
	s_cbranch_scc0 .Lp2_plain
	s_cmp_ge_i32 s45, s78
	s_cbranch_scc1 .Lp2_mix_next
	s_add_i32 s45, s45, s23
	s_cmp_lt_i32 s45, s78
	s_cbranch_scc1 .LBB0_342
	v_readlane_b32 vcc_lo, v252, 32
	s_nop 0
	s_cmp_lt_u32 vcc_lo, 64
	s_cbranch_scc1 .LBB0_412
	s_add_i32 s45, vcc_lo, 0x400
	s_branch .LBB0_342
.Lp2_mix_next:
	s_addk_i32 s45, 0x1c0
	s_cmp_lt_i32 s45, s2
	s_cbranch_scc1 .LBB0_342
	s_branch .LBB0_412

; DEVI void mixab_row4(const Params& P, int l, int base, int lt0, int tid) {
;     ...
;     for (int k = 0; k < 6; ++k) {
;       const int tt = t0 - 2 + k;
;       if (tt >= 0) {
;         const bfu* zr = z + (long)(lt0 - 2 + k) * NCOL;
;         float ac[4], ax[4];
;         load4bf(zr + 1024 + c, ac); load4bf(zr + 2048 + c, ax);
; #pragma unroll
;         for (int i = 0; i < 4; ++i) pk[k][i] = ac[i] * ax[i];
;     ...
;     for (int k = 0; k < 7; ++k) {
;       const int tt = t0 - 3 + k;
;       if (tt >= 0) {
;         load4bf(z + (long)(lt0 - 3 + k) * NCOL + 3072 + c, xk[k]);
.LBB0_351:
	s_add_i32 s74, s48, -2
	v_lshlrev_b64 v[178:179], 1, v[100:101]
	v_mad_i64_i32 v[180:181], s[42:43], s74, v191, v[74:75]
	s_add_i32 vcc_lo, s48, -1
	v_lshl_add_u64 v[180:181], v[180:181], 0, v[178:179]
	v_mad_i64_i32 v[182:183], s[42:43], vcc_lo, v191, v[74:75]
	s_add_i32 vcc_lo, s48, -3
	v_lshl_add_u64 v[182:183], v[182:183], 0, v[178:179]
	v_mad_i64_i32 v[196:197], s[42:43], vcc_lo, v191, v[74:75]
	global_load_dwordx2 v[210:211], v[180:181], off offset:2048
	global_load_dwordx2 v[214:215], v[182:183], off offset:2048
	s_mov_b64 s[42:43], 0x1000
	v_lshl_add_u64 v[196:197], v[196:197], 0, v[178:179]
	v_lshl_add_u64 v[180:181], v[180:181], 0, s[42:43]
	v_lshl_add_u64 v[182:183], v[182:183], 0, s[42:43]
	v_lshl_add_u64 v[196:197], v[196:197], 0, s[42:43]
	global_load_dwordx2 v[208:209], v[180:181], off
	global_load_dwordx2 v[212:213], v[182:183], off
	global_load_dwordx2 v[218:219], v[180:181], off offset:2048
	global_load_dwordx2 v[220:221], v[182:183], off offset:2048
	global_load_dwordx2 v[216:217], v[196:197], off offset:2048
	s_cmp_lg_u32 s64, 0
	s_cselect_b64 s[50:51], -1, 0
	s_cmp_eq_u32 s64, 0
	s_mov_b64 s[42:43], -1
	s_cbranch_scc1 .LBB0_353
	s_mov_b64 s[42:43], 0
	s_waitcnt vmcnt(0)
	v_mov_b32_e32 v2, v208
	v_mov_b32_e32 v3, v209
	v_mov_b32_e32 v0, v210
	v_mov_b32_e32 v1, v211
	v_lshlrev_b32_e32 v5, 16, v3
	v_lshlrev_b32_e32 v4, 16, v2
	v_and_b32_e32 v3, 0xffff0000, v3
	v_and_b32_e32 v2, 0xffff0000, v2
	v_and_b32_e32 v7, 0xffff0000, v1
	v_and_b32_e32 v6, 0xffff0000, v0
	v_lshlrev_b32_e32 v1, 16, v1
	v_lshlrev_b32_e32 v0, 16, v0
	v_pk_mul_f32 v[22:23], v[0:1], v[4:5]
	v_pk_mul_f32 v[2:3], v[6:7], v[2:3]

; DEVI void mixab_row4(const Params& P, int l, int base, int lt0, int tid) {
;     ...
;       const int tt = t0 - 2 + k;
;       if (tt >= 0) {
;         const bfu* zr = z + (long)(lt0 - 2 + k) * NCOL;
;         float ac[4], ax[4];
;         load4bf(zr + 1024 + c, ac); load4bf(zr + 2048 + c, ax);
; #pragma unroll
;         for (int i = 0; i < 4; ++i) pk[k][i] = ac[i] * ax[i];
.LBB0_356:
	s_and_b64 vcc, exec, s[50:51]
	s_cbranch_vccz .LBB0_358
	s_add_i32 s47, s48, -1
	s_waitcnt vmcnt(0)
	v_mov_b32_e32 v6, v212
	v_mov_b32_e32 v7, v213
	v_mov_b32_e32 v0, v214
	v_mov_b32_e32 v1, v215
	v_lshlrev_b32_e32 v9, 16, v7
	v_lshlrev_b32_e32 v8, 16, v6
	v_and_b32_e32 v7, 0xffff0000, v7
	v_and_b32_e32 v6, 0xffff0000, v6
	v_and_b32_e32 v11, 0xffff0000, v1
	v_and_b32_e32 v10, 0xffff0000, v0
	v_lshlrev_b32_e32 v1, 16, v1
	v_lshlrev_b32_e32 v0, 16, v0
	v_pk_mul_f32 v[24:25], v[0:1], v[8:9]
	v_pk_mul_f32 v[6:7], v[10:11], v[6:7]
	s_cbranch_execz .LBB0_359
	s_branch .LBB0_361

; DEVI void mixab_row4(const Params& P, int l, int base, int lt0, int tid) {
;     ...
;     for (int k = 0; k < 7; ++k) {
;       const int tt = t0 - 3 + k;
;       if (tt >= 0) {
;         load4bf(z + (long)(lt0 - 3 + k) * NCOL + 3072 + c, xk[k]);
.LBB0_367:
	s_andn2_b64 vcc, exec, s[50:51]
	s_cbranch_vccnz .LBB0_369
	s_add_i32 s47, s48, -3
	v_mov_b32_e32 v2, v216
	v_mov_b32_e32 v3, v217
	v_lshlrev_b32_e32 v52, 16, v2
	v_lshlrev_b32_e32 v53, 16, v3
	v_and_b32_e32 v13, 0xffff0000, v3
	v_and_b32_e32 v12, 0xffff0000, v2
	s_cbranch_execz .LBB0_370
	s_branch .LBB0_372

; DEVI void mixab_row4(const Params& P, int l, int base, int lt0, int tid) {
;     ...
;     for (int k = 0; k < 7; ++k) {
;       const int tt = t0 - 3 + k;
;       if (tt >= 0) {
;         load4bf(z + (long)(lt0 - 3 + k) * NCOL + 3072 + c, xk[k]);
.LBB0_372:
	s_and_b64 vcc, exec, s[50:51]
	s_cbranch_vccz .LBB0_374
	v_mov_b32_e32 v2, v218
	v_mov_b32_e32 v3, v219
	v_lshlrev_b32_e32 v50, 16, v2
	v_lshlrev_b32_e32 v51, 16, v3
	v_and_b32_e32 v9, 0xffff0000, v3
	v_and_b32_e32 v8, 0xffff0000, v2
	s_cbranch_execz .LBB0_375
	s_branch .LBB0_377

; DEVI void mixab_row4(const Params& P, int l, int base, int lt0, int tid) {
;     ...
;     for (int k = 0; k < 7; ++k) {
;       const int tt = t0 - 3 + k;
;       if (tt >= 0) {
;         load4bf(z + (long)(lt0 - 3 + k) * NCOL + 3072 + c, xk[k]);
.LBB0_377:
	s_and_b64 vcc, exec, s[50:51]
	s_cbranch_vccz .LBB0_379
	s_add_i32 s47, s48, -1
	v_mov_b32_e32 v2, v220
	v_mov_b32_e32 v3, v221
	v_lshlrev_b32_e32 v38, 16, v2
	v_lshlrev_b32_e32 v39, 16, v3
	v_and_b32_e32 v5, 0xffff0000, v3
	v_and_b32_e32 v4, 0xffff0000, v2
	s_cbranch_execz .LBB0_380
	s_branch .LBB0_382

; DEVI void mixab_row4(const Params& P, int l, int base, int lt0, int tid) {
;     ...
; #pragma unroll
;     for (int k = 0; k < 4; ++k) ld4f(P.in[9] + (long)(l * 4 + k) * 1024 + c, wb[k]);
;     ld4f(P.in[10] + (long)l * 1024 + c, bb);
; #pragma unroll
;     for (int r = 0; r < 4; ++r) {
;       float o2[4];
; #pragma unroll
;       for (int i = 0; i < 4; ++i)
;         o2[i] = wb[0][i] * xk[r][i] + wb[1][i] * xk[r + 1][i] + wb[2][i] * xk[r + 2][i] + wb[3][i] * xk[r + 3][i] + bb[i];
;       store4bf((bfu*)(P.ws + O_CB) + (long)(lt0 + r) * 1024 + c, o2);
;     }
.LBB0_382:
	v_add_co_u32_e32 v0, vcc, 0x1000, v0
	global_load_dwordx2 v[2:3], v[16:17], off offset:2048
	s_nop 0
	v_addc_co_u32_e32 v1, vcc, 0, v1, vcc
	global_load_dwordx2 v[0:1], v[0:1], off offset:2048
	global_load_dwordx2 v[222:223], v[18:19], off offset:2048
	global_load_dwordx2 v[224:225], v[20:21], off offset:2048
	global_load_dwordx4 v[14:17], v[118:119], off
	global_load_dwordx4 v[30:33], v[120:121], off
	global_load_dwordx4 v[18:21], v[122:123], off
	global_load_dwordx4 v[22:25], v[124:125], off
	global_load_dwordx4 v[26:29], v[126:127], off
	v_lshl_add_u64 v[62:63], v[128:129], 0, s[56:57]
	v_lshl_add_u64 v[48:49], v[128:129], 0, s[58:59]
	v_lshl_add_u64 v[46:47], v[128:129], 0, s[60:61]
	v_lshl_add_u64 v[40:41], v[128:129], 0, s[62:63]
	s_andn2_b64 vcc, exec, s[52:53]
	s_waitcnt vmcnt(0)
	v_and_b32_e32 v11, 0xffff0000, v3
	v_and_b32_e32 v10, 0xffff0000, v2
	v_lshlrev_b32_e32 v44, 16, v0
	v_lshlrev_b32_e32 v45, 16, v1
	v_and_b32_e32 v43, 0xffff0000, v1
	v_and_b32_e32 v42, 0xffff0000, v0
	v_lshlrev_b32_e32 v0, 16, v2
	v_lshlrev_b32_e32 v1, 16, v3
	v_mov_b32_e32 v2, v222
	v_mov_b32_e32 v3, v223
	v_lshlrev_b32_e32 v37, 16, v3
	v_lshlrev_b32_e32 v36, 16, v2
	v_and_b32_e32 v7, 0xffff0000, v3
	v_and_b32_e32 v6, 0xffff0000, v2
	v_mov_b32_e32 v2, v224
	v_mov_b32_e32 v3, v225
	v_mov_b32_e32 v54, v14
	s_waitcnt vmcnt(3)
	v_mov_b32_e32 v56, v30
	v_mov_b32_e32 v57, v32
	v_mov_b32_e32 v32, v31
	v_mov_b32_e32 v55, v16
	v_pk_mul_f32 v[58:59], v[50:51], v[56:57]
	v_mov_b32_e32 v16, v15
	v_pk_mul_f32 v[14:15], v[8:9], v[32:33]
	v_pk_fma_f32 v[58:59], v[52:53], v[54:55], v[58:59]
	s_waitcnt vmcnt(2)
	v_mov_b32_e32 v52, v18
	v_mov_b32_e32 v53, v20
	v_pk_fma_f32 v[12:13], v[12:13], v[16:17], v[14:15]
	v_mov_b32_e32 v20, v19
	v_pk_fma_f32 v[60:61], v[38:39], v[52:53], v[58:59]
	s_waitcnt vmcnt(1)
	v_mov_b32_e32 v58, v22
	v_mov_b32_e32 v59, v24
	v_pk_fma_f32 v[12:13], v[4:5], v[20:21], v[12:13]
	v_mov_b32_e32 v24, v23
	v_pk_fma_f32 v[170:171], v[58:59], v[44:45], v[60:61]
	s_waitcnt vmcnt(0)
	v_mov_b32_e32 v61, v28
	v_pk_fma_f32 v[12:13], v[24:25], v[42:43], v[12:13]
	v_mov_b32_e32 v28, v27
	v_mov_b32_e32 v60, v26
	v_pk_add_f32 v[12:13], v[12:13], v[28:29]
	v_pk_add_f32 v[170:171], v[170:171], v[60:61]
	v_and_b32_sdwa v18, v13, v95 dst_sel:DWORD dst_unused:UNUSED_PAD src0_sel:WORD_1 src1_sel:DWORD
	v_and_b32_sdwa v19, v12, v95 dst_sel:DWORD dst_unused:UNUSED_PAD src0_sel:WORD_1 src1_sel:DWORD
	v_and_b32_sdwa v14, v171, v95 dst_sel:DWORD dst_unused:UNUSED_PAD src0_sel:WORD_1 src1_sel:DWORD
	v_and_b32_sdwa v15, v170, v95 dst_sel:DWORD dst_unused:UNUSED_PAD src0_sel:WORD_1 src1_sel:DWORD
	v_add3_u32 v13, v13, v18, s39
	v_add3_u32 v12, v12, v19, s39
	v_add3_u32 v15, v170, v15, s39
	v_add3_u32 v14, v171, v14, s39
	v_and_b32_e32 v13, 0xffff0000, v13
	v_and_b32_e32 v12, 0xffff0000, v12
	v_or_b32_sdwa v13, v13, v14 dst_sel:DWORD dst_unused:UNUSED_PAD src0_sel:DWORD src1_sel:WORD_1
	v_or_b32_sdwa v12, v12, v15 dst_sel:DWORD dst_unused:UNUSED_PAD src0_sel:DWORD src1_sel:WORD_1
	global_store_dwordx2 v[62:63], v[12:13], off
	v_pk_mul_f32 v[12:13], v[38:39], v[56:57]
	v_pk_mul_f32 v[14:15], v[4:5], v[32:33]
	v_pk_fma_f32 v[12:13], v[50:51], v[54:55], v[12:13]
	v_pk_fma_f32 v[8:9], v[8:9], v[16:17], v[14:15]
	v_pk_fma_f32 v[12:13], v[52:53], v[44:45], v[12:13]
	v_pk_fma_f32 v[8:9], v[20:21], v[42:43], v[8:9]
	v_pk_fma_f32 v[12:13], v[58:59], v[0:1], v[12:13]
	v_pk_fma_f32 v[8:9], v[24:25], v[10:11], v[8:9]
	v_pk_add_f32 v[12:13], v[12:13], v[60:61]
	v_pk_add_f32 v[8:9], v[8:9], v[28:29]
	v_and_b32_sdwa v14, v13, v95 dst_sel:DWORD dst_unused:UNUSED_PAD src0_sel:WORD_1 src1_sel:DWORD
	v_and_b32_sdwa v15, v12, v95 dst_sel:DWORD dst_unused:UNUSED_PAD src0_sel:WORD_1 src1_sel:DWORD
	v_add3_u32 v12, v12, v15, s39
	v_add3_u32 v13, v13, v14, s39
	v_and_b32_sdwa v14, v9, v95 dst_sel:DWORD dst_unused:UNUSED_PAD src0_sel:WORD_1 src1_sel:DWORD
	v_and_b32_sdwa v15, v8, v95 dst_sel:DWORD dst_unused:UNUSED_PAD src0_sel:WORD_1 src1_sel:DWORD
	v_add3_u32 v9, v9, v14, s39
	v_add3_u32 v8, v8, v15, s39
	v_and_b32_e32 v9, 0xffff0000, v9
	v_and_b32_e32 v8, 0xffff0000, v8
	v_or_b32_sdwa v9, v9, v13 dst_sel:DWORD dst_unused:UNUSED_PAD src0_sel:DWORD src1_sel:WORD_1
	v_or_b32_sdwa v8, v8, v12 dst_sel:DWORD dst_unused:UNUSED_PAD src0_sel:DWORD src1_sel:WORD_1
	global_store_dwordx2 v[48:49], v[8:9], off
	v_pk_mul_f32 v[8:9], v[56:57], v[44:45]
	v_pk_mul_f32 v[12:13], v[32:33], v[42:43]
	v_pk_fma_f32 v[8:9], v[38:39], v[54:55], v[8:9]
	v_pk_fma_f32 v[4:5], v[4:5], v[16:17], v[12:13]
	v_pk_fma_f32 v[8:9], v[52:53], v[0:1], v[8:9]
	v_pk_fma_f32 v[4:5], v[20:21], v[10:11], v[4:5]
	v_pk_fma_f32 v[8:9], v[58:59], v[36:37], v[8:9]
	v_pk_fma_f32 v[4:5], v[24:25], v[6:7], v[4:5]
	v_pk_add_f32 v[8:9], v[8:9], v[60:61]
	v_pk_add_f32 v[4:5], v[4:5], v[28:29]
	v_and_b32_sdwa v12, v9, v95 dst_sel:DWORD dst_unused:UNUSED_PAD src0_sel:WORD_1 src1_sel:DWORD
	v_and_b32_sdwa v13, v8, v95 dst_sel:DWORD dst_unused:UNUSED_PAD src0_sel:WORD_1 src1_sel:DWORD
	v_add3_u32 v8, v8, v13, s39
	v_add3_u32 v9, v9, v12, s39
	v_and_b32_sdwa v12, v5, v95 dst_sel:DWORD dst_unused:UNUSED_PAD src0_sel:WORD_1 src1_sel:DWORD
	v_and_b32_sdwa v13, v4, v95 dst_sel:DWORD dst_unused:UNUSED_PAD src0_sel:WORD_1 src1_sel:DWORD
	v_add3_u32 v5, v5, v12, s39
	v_add3_u32 v4, v4, v13, s39
	v_and_b32_e32 v5, 0xffff0000, v5
	v_and_b32_e32 v4, 0xffff0000, v4
	v_or_b32_sdwa v5, v5, v9 dst_sel:DWORD dst_unused:UNUSED_PAD src0_sel:DWORD src1_sel:WORD_1
	v_or_b32_sdwa v4, v4, v8 dst_sel:DWORD dst_unused:UNUSED_PAD src0_sel:DWORD src1_sel:WORD_1
	global_store_dwordx2 v[46:47], v[4:5], off
	v_pk_mul_f32 v[4:5], v[56:57], v[0:1]
	v_pk_mul_f32 v[8:9], v[32:33], v[10:11]
	v_pk_fma_f32 v[4:5], v[54:55], v[44:45], v[4:5]
	v_lshlrev_b32_e32 v35, 16, v3
	v_lshlrev_b32_e32 v34, 16, v2
	v_pk_fma_f32 v[4:5], v[52:53], v[36:37], v[4:5]
	v_pk_fma_f32 v[8:9], v[16:17], v[42:43], v[8:9]
	v_and_b32_e32 v3, 0xffff0000, v3
	v_and_b32_e32 v2, 0xffff0000, v2
	v_pk_fma_f32 v[4:5], v[58:59], v[34:35], v[4:5]
	v_pk_fma_f32 v[8:9], v[20:21], v[6:7], v[8:9]
	v_pk_add_f32 v[4:5], v[4:5], v[60:61]
	v_pk_fma_f32 v[8:9], v[24:25], v[2:3], v[8:9]
	v_and_b32_sdwa v12, v5, v95 dst_sel:DWORD dst_unused:UNUSED_PAD src0_sel:WORD_1 src1_sel:DWORD
	v_pk_add_f32 v[8:9], v[8:9], v[28:29]
	v_and_b32_sdwa v13, v4, v95 dst_sel:DWORD dst_unused:UNUSED_PAD src0_sel:WORD_1 src1_sel:DWORD
	v_add3_u32 v4, v4, v13, s39
	v_add3_u32 v5, v5, v12, s39
	v_and_b32_sdwa v12, v9, v95 dst_sel:DWORD dst_unused:UNUSED_PAD src0_sel:WORD_1 src1_sel:DWORD
	v_and_b32_sdwa v13, v8, v95 dst_sel:DWORD dst_unused:UNUSED_PAD src0_sel:WORD_1 src1_sel:DWORD
	v_add3_u32 v9, v9, v12, s39
	v_add3_u32 v8, v8, v13, s39
	v_and_b32_e32 v9, 0xffff0000, v9
	v_and_b32_e32 v8, 0xffff0000, v8
	v_or_b32_sdwa v5, v9, v5 dst_sel:DWORD dst_unused:UNUSED_PAD src0_sel:DWORD src1_sel:WORD_1
	v_or_b32_sdwa v4, v8, v4 dst_sel:DWORD dst_unused:UNUSED_PAD src0_sel:DWORD src1_sel:WORD_1
	global_store_dwordx2 v[40:41], v[4:5], off
	s_cbranch_vccnz .LBB0_384
; DEVI void mixab_row4(const Params& P, int l, int base, int lt0, int tid) {
;     ...
;     if (t0 + 4 == T) {
;       float* cbp = ti.sample ? P.out + OUT_CBS + (long)(l * 8 + ti.seq) * 3 * 1024 + c : P.out + OUT_CBP + (long)(l * 4 + ti.seq) * 3 * 1024 + c;
; #pragma unroll
;       for (int r = 0; r < 3; ++r)
;         *reinterpret_cast<float4*>(cbp + r * 1024) = make_float4(xk[r + 4][0], xk[r + 4][1], xk[r + 4][2], xk[r + 4][3]);
;     }
	s_add_i32 s24, s24, s44
	s_and_b64 s[26:27], s[26:27], exec
	s_mov_b32 s26, 0x4110000
	s_cselect_b32 s26, s26, 0x4550000
	s_cselect_b32 s24, s24, s46
	s_add_u32 s26, s28, s26
	s_addc_u32 s27, s29, 0
	s_mul_hi_i32 s42, s24, 0x3000
	s_mulk_i32 s24, 0x3000
	s_add_u32 s26, s26, s24
	s_addc_u32 s27, s27, s42
	v_lshl_add_u64 v[12:13], v[100:101], 2, s[26:27]
	v_mov_b32_e32 v8, v0
	v_add_co_u32_e32 v0, vcc, 0x1000, v12
	v_mov_b32_e32 v9, v10
	v_mov_b32_e32 v10, v1
	v_mov_b32_e32 v4, v36
	v_mov_b32_e32 v5, v6
	v_mov_b32_e32 v6, v37
	v_addc_co_u32_e32 v1, vcc, 0, v13, vcc
	global_store_dwordx4 v[0:1], v[4:7], off
	v_mov_b32_e32 v0, v34
	v_mov_b32_e32 v1, v2
	v_add_co_u32_e32 v4, vcc, 0x2000, v12
	v_mov_b32_e32 v2, v35
	s_nop 0
	v_addc_co_u32_e32 v5, vcc, 0, v13, vcc
	global_store_dwordx4 v[12:13], v[8:11], off
	global_store_dwordx4 v[4:5], v[0:3], off

; DEVI int ltid() { int t = threadIdx.x; asm volatile("" : "+v"(t)); return t; }
; DEVI void h3_item(const Params& P, int l, int ck, int h, char* smem, int tid) {
;     ...
;   const int lane = tid & 63, w = tid >> 6, fr = lane & 15, fq = lane >> 4;
;   bfu* QT = (bfu*)smem;
;   bfu* KT = QT + 64 * 136;
;   bfu* AT = KT + 64 * 136;
;   bfu* BS = AT + 64 * 72;
;   float* bmid = (float*)(BS + 128 * 72);
;   const int d = tid & 127, hf = tid >> 7, L = ci.L, Lh = L >> 1;
;   const float lb = ((const float*)(P.ws + O_LBS))[l * 1024 + h * 128 + d];
;   const bfu* Z = (const bfu*)(P.ws + O_Z);
;   const bfu* zqb = Z + (long)ci.lt0 * NCOL + 5 * 1024 + h * 128;
;   __syncthreads();
;   {
;     uint4 vq[4], vf[4], vi[4];
; #pragma unroll
;     for (int q = 0; q < 4; ++q) {
;       const int idx = tid + 256 * q;
;       const int sr = (idx & 15) | (((idx >> 8) & 3) << 4), c16 = ((idx >> 4) & 3) | (((idx >> 6) & 3) << 2);
; DEVI void phase4(const Params& P, int l, int pass, char* smem) {
;   const int tid = ltid();
;   const int ntok = pass ? 8192 : 8448;
;   const int nck = pass ? 128 : 136;
;   const int nH = nck * 8;
;   const int nA = (ntok / 128) * 4;
;   const int nM = ntok / 128, nT = nM * 8;
;   for (int id = blockIdx.x; id < nA + nH + nT; id += gridDim.x) {
.LBB0_501:
	s_mov_b32 s91, 0x20000
	s_or_b64 exec, exec, s[26:27]
	s_barrier
	s_cmp_eq_u32 s90, 0
	s_cselect_b64 s[26:27], -1, 0
	s_and_b64 s[40:41], s[26:27], exec
	s_movk_i32 s1, 0x440
	s_cselect_b32 s24, 0x42, 64
	s_cselect_b32 s2, s1, 0x400
	s_lshl_b32 s1, s24, 2
	s_lshl_b32 s24, s24, 3
	s_or_b32 s60, s1, s2
	s_or_b32 s44, s60, s24
	v_mov_b32_e32 v91, v93
	s_cmp_ge_i32 s74, s44
	s_cbranch_scc1 .LBB0_691
	v_lshlrev_b32_e32 v101, 4, v91
	v_add_u32_e32 v107, 0x3000, v101
	v_ashrrev_i32_e32 v18, 7, v107
	v_xor_b32_e32 v17, v18, v91
	v_lshlrev_b32_e32 v17, 3, v17
	v_and_b32_e32 v22, 56, v17
	v_and_b32_e32 v17, 15, v91
	v_lshrrev_b32_e32 v23, 1, v91
	s_mov_b32 s2, 0x1ffffc0
	v_and_or_b32 v24, v23, s2, v17
	v_lshrrev_b32_e32 v3, 4, v91
	v_bfe_u32 v7, v91, 4, 2
	v_and_b32_e32 v25, 7, v91
	v_lshlrev_b32_e32 v164, 7, v24
	v_lshlrev_b32_e32 v24, 7, v91
	v_bitop3_b32 v26, v3, v25, 3 bitop3:0x6c
	v_and_b32_e32 v165, 0x2780, v24
	v_bitop3_b32 v24, v7, v25, 4 bitop3:0x36
	v_lshrrev_b32_e32 v25, 2, v91
	v_and_b32_e32 v25, 12, v25
	s_mov_b32 s2, 0x7fffc0
	v_lshlrev_b32_e32 v166, 4, v24
	v_and_b32_e32 v24, 64, v91
	v_and_or_b32 v25, v23, s2, v25
	v_and_b32_e32 v3, 48, v3
	v_lshlrev_b32_e32 v109, 4, v26
	v_lshlrev_b32_e32 v26, 2, v24
	v_lshlrev_b32_e32 v24, 2, v17
	v_lshlrev_b32_e32 v25, 9, v25
	v_and_b32_e32 v100, 0x78, v23
	v_or_b32_e32 v171, v3, v17
	v_add_u32_e32 v23, 0x100, v91
	v_bitop3_b32 v173, v3, 32, v17 bitop3:0x36
	v_add_u32_e32 v3, 0x300, v91
	v_or3_b32 v167, v26, v24, v25
	v_lshlrev_b32_e32 v25, 2, v91
	v_lshrrev_b32_e32 v23, 4, v23
	v_lshrrev_b32_e32 v3, 4, v3
	v_and_b32_e32 v168, 0x7c, v25
	v_and_or_b32 v172, v23, 48, v17
	v_and_or_b32 v174, v3, 48, v17
	v_lshlrev_b32_e32 v3, 1, v100
	v_mul_u32_u24_e32 v23, 0x88, v171
	v_mul_u32_u24_e32 v25, 0x48, v100
	s_movk_i32 s2, 0x8e
	v_lshl_add_u32 v175, v23, 1, v3
	v_lshlrev_b32_e32 v23, 1, v171
	v_lshlrev_b32_e32 v25, 1, v25
	v_mad_u32_u24 v26, v100, s2, v3
	v_or_b32_e32 v176, v23, v25
	v_add_u32_e32 v177, v26, v23
	v_mul_u32_u24_e32 v23, 0x88, v172
	v_lshl_add_u32 v178, v23, 1, v3
	v_lshlrev_b32_e32 v23, 1, v172
	v_or_b32_e32 v179, v23, v25
	v_add_u32_e32 v180, v26, v23
	v_mul_u32_u24_e32 v23, 0x88, v173
	v_lshl_add_u32 v181, v23, 1, v3
	v_lshlrev_b32_e32 v23, 1, v173
	v_or_b32_e32 v182, v23, v25
	v_add_u32_e32 v183, v26, v23
	v_mul_u32_u24_e32 v23, 0x88, v174
	s_movk_i32 s2, 0x7f
	v_ashrrev_i32_e32 v31, 7, v91
	v_lshl_add_u32 v196, v23, 1, v3
	v_lshlrev_b32_e32 v23, 1, v174
	v_cmp_lt_u32_e64 s[4:5], s2, v91
	s_movk_i32 s2, 0x880
	v_and_b32_e32 v27, 0x7f, v91
	v_or_b32_e32 v197, v23, v25
	v_add_u32_e32 v198, v26, v23
	v_mul_lo_u32 v23, v31, s2
	v_or_b32_e32 v23, v23, v27
	v_lshlrev_b32_e32 v200, 1, v23
	v_ashrrev_i32_e32 v23, 2, v91
	v_and_b32_e32 v25, -16, v23
	v_writelane_b32 v252, s4, 37
	v_lshl_or_b32 v201, v7, 2, v25
	v_or_b32_e32 v202, 1, v201
	v_writelane_b32 v252, s5, 38
	v_cmp_gt_i32_e64 s[4:5], v17, v201
	v_cmp_gt_i32_e64 s[6:7], v17, v202
	v_or_b32_e32 v203, 2, v201
	v_writelane_b32 v252, s4, 34
	v_or_b32_e32 v204, 3, v201
	v_or_b32_e32 v29, 16, v17
	v_writelane_b32 v252, s5, 35
	v_writelane_b32 v252, s6, 39
	v_or_b32_e32 v30, 32, v17
	v_cmp_gt_i32_e64 s[64:65], v30, v204
	v_writelane_b32 v252, s7, 40
	v_cmp_gt_i32_e64 s[6:7], v17, v203
	s_lshl_b32 s50, s0, 7
	v_bfi_b32 v23, -16, v23, v91
	v_writelane_b32 v252, s6, 41
	v_lshlrev_b32_e32 v26, 4, v7
	v_or_b32_e32 v32, 48, v17
	v_writelane_b32 v252, s7, 42
	v_cmp_gt_i32_e64 s[6:7], v17, v204
	s_movk_i32 s4, 0x90
	s_lshl_b32 s45, s0, 6
	v_writelane_b32 v252, s6, 43
	v_ashrrev_i32_e32 v25, 1, v91
	s_ashr_i32 s51, s50, 31
	v_writelane_b32 v252, s7, 44
	v_cmp_gt_i32_e64 s[6:7], v29, v201
	v_cmp_gt_i32_e64 s[66:67], v32, v201
	v_cmp_gt_i32_e64 s[40:41], v32, v202
	v_writelane_b32 v252, s6, 45
	v_cmp_gt_i32_e64 s[42:43], v32, v203
	v_cmp_gt_i32_e64 s[62:63], v32, v204
	v_writelane_b32 v252, s7, 46
	v_cmp_gt_i32_e64 s[6:7], v29, v202
	v_mad_u64_u32 v[110:111], s[46:47], v23, s4, v[26:27]
	s_nop 0
	v_writelane_b32 v252, s6, 47
	v_lshlrev_b32_e32 v32, 7, v25
	s_and_b64 s[26:27], s[26:27], exec
	v_writelane_b32 v252, s7, 48
	v_cmp_gt_i32_e64 s[6:7], v29, v203
	v_readlane_b32 s52, v253, 6
	v_mul_lo_u32 v7, v201, s4
	v_writelane_b32 v252, s6, 49
	v_ashrrev_i32_e32 v33, 31, v32
	v_readlane_b32 s58, v253, 12
	v_writelane_b32 v252, s7, 50
	v_cmp_gt_i32_e64 s[6:7], v29, v204
	v_lshlrev_b32_e32 v29, 5, v91
	v_ashrrev_i32_e32 v8, 3, v91
	v_writelane_b32 v252, s6, 51
	v_add_u32_e32 v103, 0x1000, v101
	v_lshlrev_b64 v[32:33], 1, v[32:33]
	v_writelane_b32 v252, s7, 52
	v_cmp_gt_i32_e64 s[6:7], v30, v201
	v_readlane_b32 s59, v253, 13
	v_ashrrev_i32_e32 v9, 31, v8
; DEVI void phase4(const Params& P, int l, int pass, char* smem) {
;     ...
;   for (int id = blockIdx.x; id < nA + nH + nT; id += gridDim.x) {
;     if (id < nA) apply_item(P, l, pass, id, tid);
;     else if (id < nA + nH) { int q = id - nA; h3_item(P, l, q >> 3, q & 7, smem, tid); }
;     else { int pm, pn; tile_rc_m(id - nA - nH, nM, 8, pm, pn); p6_branch<0, 0, 0>(P, pm, pn, nullptr, smem, tid); }
;   }
	v_writelane_b32 v252, s6, 53
	v_ashrrev_i32_e32 v10, 7, v103
	v_xor_b32_e32 v2, v8, v91
	v_writelane_b32 v252, s7, 54
	v_cmp_gt_i32_e64 s[6:7], v30, v202
	v_lshlrev_b64 v[0:1], 10, v[8:9]
	v_ashrrev_i32_e32 v11, 31, v10
	v_writelane_b32 v252, s6, 55
	v_add_u32_e32 v105, 0x2000, v101
	v_lshlrev_b32_e32 v28, 1, v17
	v_writelane_b32 v252, s7, 56
	v_cmp_gt_i32_e64 s[6:7], v30, v203
	v_and_b32_e32 v30, 32, v29
	v_lshlrev_b32_e32 v88, 1, v30
	v_writelane_b32 v252, s6, 57
	v_mad_u64_u32 v[112:113], s[46:47], v25, s4, v[88:89]
	s_nop 0
	v_writelane_b32 v252, s7, 58
	s_cselect_b32 s46, 0, 0x2100
	s_lshl_b32 s47, s0, 3
	s_lshl_b32 s48, s0, 2
	v_readlane_b32 s4, v252, 10
	s_lshl_b64 s[26:27], s[50:51], 2
	v_readlane_b32 s5, v252, 11
	s_add_u32 s26, s58, s26
	s_addc_u32 s27, s59, s27
	v_lshl_add_u64 v[34:35], s[4:5], 0, v[32:33]
	v_mov_b32_e32 v25, v89
	v_readlane_b32 s4, v252, 12
	v_lshl_add_u64 v[118:119], s[26:27], 0, v[24:25]
	v_mov_b32_e32 v29, v89
	v_readlane_b32 s5, v252, 13
	v_lshlrev_b64 v[24:25], 11, v[8:9]
	v_bitop3_b32 v8, v8, 7, v91 bitop3:0x48
	v_xor_b32_e32 v6, v10, v91
	v_lshlrev_b64 v[4:5], 10, v[10:11]
	v_ashrrev_i32_e32 v12, 7, v105
	v_lshl_add_u64 v[120:121], s[4:5], 0, v[28:29]
	v_lshl_or_b32 v24, v8, 4, v24
	v_readlane_b32 s4, v252, 25
	v_lshlrev_b64 v[8:9], 11, v[10:11]
	v_bitop3_b32 v10, v10, 7, v91 bitop3:0x48
	v_ashrrev_i32_e32 v13, 31, v12
	v_readlane_b32 s5, v252, 26
	v_lshl_or_b32 v8, v10, 4, v8
	v_bitop3_b32 v10, v12, 7, v91 bitop3:0x48
	v_lshl_add_u64 v[124:125], s[4:5], 0, v[8:9]
	v_lshlrev_b64 v[8:9], 11, v[12:13]
	v_ashrrev_i32_e32 v19, 31, v18
	v_lshl_or_b32 v8, v10, 4, v8
	v_lshl_add_u64 v[126:127], s[4:5], 0, v[8:9]
	v_lshlrev_b64 v[8:9], 11, v[18:19]
	v_bitop3_b32 v10, v18, 7, v91 bitop3:0x48
	v_xor_b32_e32 v16, v12, v91
	s_movk_i32 s2, 0x110
	v_lshl_or_b32 v8, v10, 4, v8
	v_lshlrev_b32_e32 v2, 3, v2
	v_lshlrev_b32_e32 v6, 3, v6
	v_lshlrev_b32_e32 v16, 3, v16
	v_mul_lo_u32 v36, v23, s2
	v_mul_u32_u24_e32 v23, 0x90, v27
	v_mul_lo_u32 v42, v201, s2
	v_lshl_add_u64 v[128:129], s[4:5], 0, v[8:9]
	v_lshlrev_b32_e32 v8, 6, v31
	s_mov_b32 s2, 0xac00
	v_and_b32_e32 v2, 56, v2
	v_and_b32_e32 v6, 56, v6
	v_lshlrev_b64 v[14:15], 10, v[12:13]
	v_and_b32_e32 v16, 56, v16
	v_lshlrev_b64 v[20:21], 10, v[18:19]
	v_mul_u32_u24_e32 v37, 0x110, v17
	v_mul_u32_u24_e32 v38, 0x110, v171
	v_mul_u32_u24_e32 v39, 0x110, v172
	v_mul_u32_u24_e32 v40, 0x110, v173
	v_mul_u32_u24_e32 v41, 0x110, v174
	v_mul_u32_u24_e32 v17, 0x90, v17
	v_lshlrev_b32_e32 v113, 1, v27
	v_add3_u32 v206, v23, v8, s2
	v_and_b32_e32 v8, 0xffffff80, v91
	v_lshlrev_b32_e32 v169, 2, v168
	v_lshl_or_b32 v170, s0, 10, v27
	v_mul_u32_u24_e32 v102, 0x3000, v171
	v_mul_u32_u24_e32 v104, 0x3000, v172
	v_mul_u32_u24_e32 v106, 0x3000, v173
	v_mul_u32_u24_e32 v108, 0x3000, v174
	v_lshlrev_b32_e32 v199, 2, v27
	v_lshlrev_b32_e32 v111, 2, v30
	s_movk_i32 s37, 0x110
	v_lshl_add_u64 v[114:115], v[34:35], 0, v[88:89]
	v_lshl_add_u64 v[116:117], s[30:31], 0, v[32:33]
	v_lshl_add_u64 v[122:123], s[4:5], 0, v[24:25]
	v_add_u32_e32 v205, 0xfffff780, v113
	v_add_u32_e32 v207, 0xf400, v8
	v_lshl_or_b32 v208, v31, 12, v27
	v_add_u32_e32 v209, 0xf500, v8
	v_lshlrev_b64 v[130:131], 1, v[0:1]
	v_lshlrev_b32_e32 v132, 1, v2
	v_lshlrev_b64 v[134:135], 1, v[4:5]
	v_lshlrev_b32_e32 v136, 1, v6
	v_lshlrev_b64 v[138:139], 1, v[14:15]
	v_lshlrev_b32_e32 v140, 1, v16
	v_lshlrev_b64 v[142:143], 1, v[20:21]
	v_lshlrev_b32_e32 v144, 1, v22
	v_add_u32_e32 v210, v36, v26
	v_add_u32_e32 v211, v26, v37
	v_add_u32_e32 v212, v28, v7
	v_add_u32_e32 v213, v3, v38
	v_add_u32_e32 v214, v3, v39
	v_add_u32_e32 v215, v3, v40
	v_add_u32_e32 v216, v3, v41
	v_add_u32_e32 v217, v26, v17
	v_lshlrev_b32_e32 v146, 1, v30
	v_add_u32_e32 v218, v28, v42
	v_readlane_b32 s49, v252, 16
	s_mov_b32 s2, s74
	v_readlane_b32 s53, v253, 7
	v_readlane_b32 s54, v253, 8
	v_readlane_b32 s55, v253, 9
	v_readlane_b32 s56, v253, 10
	v_readlane_b32 s57, v253, 11
	s_getreg_b32 vcc_lo, hwreg(HW_REG_XCC_ID, 0, 4)
	s_nop 1
	s_bitcmp1_b32 vcc_lo, 0
	s_cbranch_scc0 .LBB0_504
.Lp4_rev_init:
	s_add_i32 vcc_lo, s2, s23
	s_cmp_lt_i32 vcc_lo, s44
	s_cbranch_scc0 .LBB0_504
	s_mov_b32 s2, vcc_lo
	v_readlane_b32 vcc_hi, v252, 17
	s_nop 3
	s_add_i32 s49, s49, vcc_hi
	s_branch .Lp4_rev_init
.LBB0_503:
	v_readlane_b32 s4, v252, 17
	s_getreg_b32 vcc_lo, hwreg(HW_REG_XCC_ID, 0, 4)
	s_nop 1
	s_bitcmp1_b32 vcc_lo, 0
	s_cbranch_scc1 .Lp4_back
	s_add_i32 s2, s2, s23
	s_add_i32 s49, s49, s4
	s_cmp_lt_i32 s2, s44
	s_cbranch_scc0 .LBB0_690
	s_branch .LBB0_504
.Lp4_back:
	s_sub_i32 s2, s2, s23
	s_sub_i32 s49, s49, s4
	s_cmp_ge_i32 s2, 0
	s_cbranch_scc0 .LBB0_690
